# topk rank loop: key prefetch one iteration ahead + compare/addc pipelined over three SGPR pairs (no s_nop)
# baseline (speedup 1.0000x reference)
; #define LAS __attribute__((address_space(3)))
; __device__ __forceinline__ void nsa_item(LAS unsigned char* lds, const NsaPtrs& P, int b, int g, int qb, int tid) {
;     ...
;         int tid_k = tid; asm volatile("" : "+v"(tid_k)); const int tk = tid_k >> 3, part = tid_k & 7;
;         unsigned v[16]; int cnt[16];
;         LAS unsigned* impu = (LAS unsigned*)imp;
; #pragma unroll
;         for (int jj = 0; jj < 16; ++jj) { const int j = part * 16 + jj; const bool forced = (j == 0) || (j == qb) || (j == qb - 1);
;             const unsigned key = forced ? 0x7fffff80u : (__float_as_uint(fmaxf(imp[tk * ISTR + j], 0.f)) & 0xffffff80u); v[jj] = key | (unsigned)(127 - j); cnt[jj] = 0; }
;         __syncthreads();
; #pragma unroll
;         for (int jj = 0; jj < 16; ++jj) impu[tk * ISTR + part * 16 + jj] = v[jj];
;         __syncthreads();
;         for (int k = 0; k <= qb; ++k) { const unsigned vk = impu[tk * ISTR + k];
; #pragma unroll
;             for (int jj = 0; jj < 16; ++jj) cnt[jj] += (vk > v[jj]) ? 1 : 0; }
;         unsigned bits = 0u;
; #pragma unroll
;         for (int jj = 0; jj < 16; ++jj) { const int j = part * 16 + jj; if (j <= qb && cnt[jj] < 16) bits |= (1u << jj); }
;         ((LAS unsigned short*)(lds + OFF_SEL))[tk * 8 + part] = (unsigned short)bits;
;     }
.LBB0_1071:
	s_or_b64 exec, exec, s[6:7]
	v_sub_u32_e32 v0, v2, v47
	v_sub_u32_e32 v12, v12, v37
	v_sub_u32_e32 v3, v3, v33
	v_add_u32_e32 v2, 0x7f, v0
	v_sub_u32_e32 v0, v16, v46
	v_sub_u32_e32 v15, v15, v44
	v_sub_u32_e32 v14, v14, v41
	v_sub_u32_e32 v13, v13, v39
	v_add_u32_e32 v24, 0x7f, v12
	v_sub_u32_e32 v11, v11, v35
	v_sub_u32_e32 v5, v5, v7
	v_add_u32_e32 v12, 0x7f, v3
	v_sub_u32_e32 v3, v19, v48
	s_add_i32 s10, s72, 1
	v_add_u32_e32 v16, 0x7f, v0
	v_sub_u32_e32 v0, v17, v45
	v_add_u32_e32 v18, 0x7f, v15
	v_sub_u32_e32 v6, v6, v42
	v_add_u32_e32 v20, 0x7f, v14
	v_sub_u32_e32 v4, v4, v40
	v_add_u32_e32 v22, 0x7f, v13
	v_sub_u32_e32 v10, v10, v38
	v_sub_u32_e32 v8, v8, v36
	v_add_u32_e32 v26, 0x7f, v11
	v_sub_u32_e32 v9, v9, v34
	v_add_u32_e32 v28, 0x7f, v5
	v_add_u32_e32 v30, 0x7f, v3
	s_cmp_lg_u32 s72, 0
	v_add_u32_e32 v0, 0x7f, v0
	v_add_u32_e32 v6, 0x7f, v6
	v_add_u32_e32 v4, 0x7f, v4
	v_add_u32_e32 v10, 0x7f, v10
	v_add_u32_e32 v8, 0x7f, v8
	v_add_u32_e32 v14, 0x7f, v9
	v_lshl_add_u32 v17, v1, 6, v49
	v_mov_b32_e32 v13, v28
	v_mov_b32_e32 v15, v26
	v_mov_b32_e32 v9, v24
	v_mov_b32_e32 v11, v22
	v_mov_b32_e32 v5, v20
	v_mov_b32_e32 v7, v18
	v_mov_b32_e32 v1, v16
	v_mov_b32_e32 v3, v30
	s_cselect_b64 s[8:9], -1, 0
	s_cmp_eq_u32 s72, 0
	s_mov_b32 s11, 0
	s_barrier
	ds_write_b128 v17, v[12:15]
	ds_write_b128 v17, v[8:11] offset:16
	ds_write_b128 v17, v[4:7] offset:32
	ds_write_b128 v17, v[0:3] offset:48
	s_waitcnt lgkmcnt(0)
	s_barrier
	s_cbranch_scc1 .LBB0_1075
	s_and_b32 s11, s10, 0xfe
	v_mov_b32_e32 v17, v30
	v_mov_b32_e32 v1, v12
	v_mov_b32_e32 v19, v28
	v_mov_b32_e32 v3, v14
	v_mov_b32_e32 v21, v26
	v_mov_b32_e32 v5, v8
	v_mov_b32_e32 v23, v24
	v_mov_b32_e32 v7, v10
	v_mov_b32_e32 v25, v22
	v_mov_b32_e32 v9, v4
	v_mov_b32_e32 v27, v20
	v_mov_b32_e32 v11, v6
	v_mov_b32_e32 v29, v18
	v_mov_b32_e32 v13, v0
	v_mov_b32_e32 v31, v16
	v_mov_b32_e32 v15, v2
	v_mov_b32_e32 v50, 0
	s_mov_b32 s6, s11
	v_mov_b32_e32 v51, 0
	v_mov_b32_e32 v52, 0
	v_mov_b32_e32 v53, 0
	v_mov_b32_e32 v54, 0
	v_mov_b32_e32 v55, 0
	v_mov_b32_e32 v56, 0
	v_mov_b32_e32 v57, 0
	v_mov_b32_e32 v58, 0
	v_mov_b32_e32 v59, 0
	v_mov_b32_e32 v60, 0
	v_mov_b32_e32 v61, 0
	v_mov_b32_e32 v62, 0
	v_mov_b32_e32 v63, 0
	v_mov_b32_e32 v64, 0
	v_mov_b32_e32 v65, 0
	v_mov_b32_e32 v66, 0
	v_mov_b32_e32 v67, 0
	v_mov_b32_e32 v68, 0
	v_mov_b32_e32 v69, 0
	v_mov_b32_e32 v70, 0
	v_mov_b32_e32 v71, 0
	v_mov_b32_e32 v72, 0
	v_mov_b32_e32 v73, 0
	v_mov_b32_e32 v74, 0
	v_mov_b32_e32 v75, 0
	v_mov_b32_e32 v76, 0
	v_mov_b32_e32 v77, 0
	v_mov_b32_e32 v78, 0
	v_mov_b32_e32 v79, 0
	v_mov_b32_e32 v80, 0
	v_mov_b32_e32 v81, 0
	ds_read_b64 v[82:83], v49
	v_add_u32_e32 v49, 8, v49
.LBB0_1073:
	s_add_i32 s6, s6, -2
	s_waitcnt lgkmcnt(0)
	v_mov_b32_e32 v84, v82
	v_mov_b32_e32 v85, v83
	ds_read_b64 v[82:83], v49
	v_add_u32_e32 v49, 8, v49
	s_cmp_lg_u32 s6, 0
	v_cmp_gt_u32_e64 s[12:13], v85, v1
	v_cmp_gt_u32_e64 s[14:15], v84, v12
	v_cmp_gt_u32_e64 s[20:21], v85, v19
	v_addc_co_u32_e64 v81, s[60:61], 0, v81, s[12:13]
	v_cmp_gt_u32_e64 s[12:13], v84, v28
	v_addc_co_u32_e64 v80, s[60:61], 0, v80, s[14:15]
	v_cmp_gt_u32_e64 s[14:15], v85, v3
	v_addc_co_u32_e64 v79, s[60:61], 0, v79, s[20:21]
	v_cmp_gt_u32_e64 s[20:21], v84, v14
	v_addc_co_u32_e64 v78, s[60:61], 0, v78, s[12:13]
	v_cmp_gt_u32_e64 s[12:13], v85, v21
	v_addc_co_u32_e64 v77, s[60:61], 0, v77, s[14:15]
	v_cmp_gt_u32_e64 s[14:15], v84, v26
	v_addc_co_u32_e64 v76, s[60:61], 0, v76, s[20:21]
	v_cmp_gt_u32_e64 s[20:21], v85, v5
	v_addc_co_u32_e64 v75, s[60:61], 0, v75, s[12:13]
	v_cmp_gt_u32_e64 s[12:13], v84, v8
	v_addc_co_u32_e64 v74, s[60:61], 0, v74, s[14:15]
	v_cmp_gt_u32_e64 s[14:15], v85, v23
	v_addc_co_u32_e64 v73, s[60:61], 0, v73, s[20:21]
	v_cmp_gt_u32_e64 s[20:21], v84, v24
	v_addc_co_u32_e64 v72, s[60:61], 0, v72, s[12:13]
	v_cmp_gt_u32_e64 s[12:13], v85, v7
	v_addc_co_u32_e64 v71, s[60:61], 0, v71, s[14:15]
	v_cmp_gt_u32_e64 s[14:15], v84, v10
	v_addc_co_u32_e64 v70, s[60:61], 0, v70, s[20:21]
	v_cmp_gt_u32_e64 s[20:21], v85, v25
	v_addc_co_u32_e64 v69, s[60:61], 0, v69, s[12:13]
	v_cmp_gt_u32_e64 s[12:13], v84, v22
	v_addc_co_u32_e64 v68, s[60:61], 0, v68, s[14:15]
	v_cmp_gt_u32_e64 s[14:15], v85, v9
	v_addc_co_u32_e64 v67, s[60:61], 0, v67, s[20:21]
	v_cmp_gt_u32_e64 s[20:21], v84, v4
	v_addc_co_u32_e64 v66, s[60:61], 0, v66, s[12:13]
	v_cmp_gt_u32_e64 s[12:13], v85, v27
	v_addc_co_u32_e64 v65, s[60:61], 0, v65, s[14:15]
	v_cmp_gt_u32_e64 s[14:15], v84, v20
	v_addc_co_u32_e64 v64, s[60:61], 0, v64, s[20:21]
	v_cmp_gt_u32_e64 s[20:21], v85, v11
	v_addc_co_u32_e64 v63, s[60:61], 0, v63, s[12:13]
	v_cmp_gt_u32_e64 s[12:13], v84, v6
	v_addc_co_u32_e64 v62, s[60:61], 0, v62, s[14:15]
	v_cmp_gt_u32_e64 s[14:15], v85, v29
	v_addc_co_u32_e64 v61, s[60:61], 0, v61, s[20:21]
	v_cmp_gt_u32_e64 s[20:21], v84, v18
	v_addc_co_u32_e64 v60, s[60:61], 0, v60, s[12:13]
	v_cmp_gt_u32_e64 s[12:13], v85, v13
	v_addc_co_u32_e64 v59, s[60:61], 0, v59, s[14:15]
	v_cmp_gt_u32_e64 s[14:15], v84, v0
	v_addc_co_u32_e64 v58, s[60:61], 0, v58, s[20:21]
	v_cmp_gt_u32_e64 s[20:21], v85, v31
	v_addc_co_u32_e64 v57, s[60:61], 0, v57, s[12:13]
	v_cmp_gt_u32_e64 s[12:13], v84, v16
	v_addc_co_u32_e64 v56, s[60:61], 0, v56, s[14:15]
	v_cmp_gt_u32_e64 s[14:15], v85, v15
	v_addc_co_u32_e64 v55, s[60:61], 0, v55, s[20:21]
	v_cmp_gt_u32_e64 s[20:21], v84, v2
	v_addc_co_u32_e64 v54, s[60:61], 0, v54, s[12:13]
	v_cmp_gt_u32_e64 s[12:13], v85, v17
	v_addc_co_u32_e64 v53, s[60:61], 0, v53, s[14:15]
	v_cmp_gt_u32_e64 s[14:15], v84, v30
	s_nop 1
	v_addc_co_u32_e64 v52, s[60:61], 0, v52, s[20:21]
	v_addc_co_u32_e64 v51, s[60:61], 0, v51, s[12:13]
	v_addc_co_u32_e64 v50, s[60:61], 0, v50, s[14:15]
	s_cbranch_scc1 .LBB0_1073
	s_cmp_lg_u32 s10, s11
	v_add_u32_e32 v1, v50, v51
	v_add_u32_e32 v3, v52, v53
	v_add_u32_e32 v5, v54, v55
	v_add_u32_e32 v7, v56, v57
	v_add_u32_e32 v9, v58, v59
	v_add_u32_e32 v11, v60, v61
	v_add_u32_e32 v13, v62, v63
	v_add_u32_e32 v15, v64, v65
	v_add_u32_e32 v17, v66, v67
	v_add_u32_e32 v19, v68, v69
	v_add_u32_e32 v21, v70, v71
	v_add_u32_e32 v23, v72, v73
	v_add_u32_e32 v25, v74, v75
	v_add_u32_e32 v27, v76, v77
	v_add_u32_e32 v29, v78, v79
	v_add_u32_e32 v31, v80, v81
	s_cselect_b64 s[6:7], -1, 0
	s_and_b64 vcc, exec, s[6:7]
	s_cbranch_vccnz .LBB0_1076
	s_branch .LBB0_1078
